# speedup vs baseline: 1.0150x; 1.0102x over previous
; template <int NT, int BM, int BN, bool PLAIN, int NSTAGE, bool EPI_LDS>
; __device__ __forceinline__ void gemm_tile(const Params& p, const GemmDesc& g, bf16_t* lds, const int tid) {
;     ...
;   const int r0 = tid >> 3, c0 = tid & 7;
;   unsigned aoff[PLAIN ? 1 : NA];
;   const char* abase = (const char*)g.A;
;   if (PLAIN) {
;     abase = (const char*)(g.A + (long)m0 * g.lda_lo);
;     aoff[0] = (unsigned)((r0 * (int)g.lda_lo + c0 * 8) * 2);
;   } else {
; #pragma unroll
;     for (int i = 0; i < NA; ++i) {
;       int ra = m0 + r0 + RP * i;
;       int rlo = ra & g.rmask; rlo = rlo < g.rclamp ? rlo : g.rclamp;
;       aoff[i] = (unsigned)(((long)rlo * g.lda_lo + (long)(ra >> g.rshift) * g.lda_hi + c0 * 8) * 2);
;     }
;   }
;   const char* bbase = (const char*)(g.Bt + (long)n0 * g.ldb);
;   const unsigned boff = (unsigned)((r0 * (int)g.ldb + c0 * 8) * 2);
;   const long astepP = (long)RP * g.lda_lo * 2, bstepP = (long)RP * g.ldb * 2;
;   u32x4 ra4[NA], rb4[NB];
;   f32x4 acc[MI][NI];
; #pragma unroll
;   for (int i = 0; i < MI; ++i)
; #pragma unroll
;     for (int j = 0; j < NI; ++j) acc[i][j] = f32x4{0.f, 0.f, 0.f, 0.f};
;   const int nk = g.K >> 6;
;     ...
;   constexpr int STAGE_BYTES = (BM + BN) * 128;
;   char* const ldsb = (char*)lds;
;   const unsigned woff = (unsigned)(((r0 >> 4) * 2 + (c0 >> 2)) * 1024 + (((((r0 & 15) ^ (c0 >> 2)) * 64) + (c0 & 3) * 16) ^ (((r0 & 15) >> 3) << 5)));
;   const unsigned roff = (unsigned)(((fr * 64) + fq * 16) ^ ((fr >> 3) << 5));
;   const int roff1d = (int)((((fr ^ 1) * 64 + fq * 16) ^ ((fr >> 3) << 5))) - (int)roff;
;     ...
;     GLOAD(0)
;     __syncthreads();
;     LWRITE(0)
;     if (nk > 1) GLOAD(1)
;     __syncthreads();
.LBB0_896:
	v_lshrrev_b32_e32 v0, 6, v224
	v_and_b32_e32 v2, 63, v224
	v_readfirstlane_b32 s57, v0
	v_lshrrev_b32_e32 v3, 3, v2
	v_bfe_u32 v4, v2, 4, 2
	v_and_b32_e32 v5, 3, v2
	v_xor_b32_e32 v4, v4, v5
	v_lshlrev_b32_e32 v4, 4, v4
	v_bfe_u32 v5, v2, 2, 1
	v_lshl_or_b32 v4, v5, 6, v4
	v_xor_b32_e32 v5, 64, v4
	s_cmp_ge_u32 s57, 4
	s_cselect_b32 s58, s26, s52
	s_cselect_b32 s59, s41, s42
	s_cselect_b32 s60, s28, s30
	s_cselect_b32 s61, s29, s31
	s_and_b32 s62, s57, 3
	s_lshl_b32 s62, s62, 6
	s_add_i32 s59, s59, s62
	s_mul_i32 s59, s59, s58
	s_lshl_b32 s58, s58, 1
	s_lshl_b32 s59, s59, 1
	s_add_u32 s60, s60, s59
	s_addc_u32 s61, s61, 0
	v_mul_lo_u32 v3, v3, s58
	s_lshl_b32 s62, s58, 3
	v_add_u32_e32 v162, v3, v4
	v_add3_u32 v163, v3, v5, s62
	s_lshl_b32 s62, s58, 4
	v_add_u32_e32 v164, s62, v162
	v_add_u32_e32 v165, s62, v163
	v_add_u32_e32 v166, s62, v164
	v_add_u32_e32 v167, s62, v165
	v_add_u32_e32 v168, s62, v166
	v_add_u32_e32 v169, s62, v167
	s_lshl_b32 s57, s57, 13
	s_barrier
	s_mov_b32 m0, s57
	s_nop 0
	global_load_lds_dwordx4 v162, s[60:61]
	s_add_u32 m0, m0, 0x400
	s_nop 0
	global_load_lds_dwordx4 v163, s[60:61]
	s_add_u32 m0, m0, 0x400
	s_nop 0
	global_load_lds_dwordx4 v164, s[60:61]
	s_add_u32 m0, m0, 0x400
	s_nop 0
	global_load_lds_dwordx4 v165, s[60:61]
	s_add_u32 m0, m0, 0x400
	s_nop 0
	global_load_lds_dwordx4 v166, s[60:61]
	s_add_u32 m0, m0, 0x400
	s_nop 0
	global_load_lds_dwordx4 v167, s[60:61]
	s_add_u32 m0, m0, 0x400
	s_nop 0
	global_load_lds_dwordx4 v168, s[60:61]
	s_add_u32 m0, m0, 0x400
	s_nop 0
	global_load_lds_dwordx4 v169, s[60:61]
	s_add_u32 s60, s60, 0x80
	s_addc_u32 s61, s61, 0
	s_add_u32 m0, s57, 0x10000
	s_nop 0
	global_load_lds_dwordx4 v162, s[60:61]
	s_add_u32 m0, m0, 0x400
	s_nop 0
	global_load_lds_dwordx4 v163, s[60:61]
	s_add_u32 m0, m0, 0x400
	s_nop 0
	global_load_lds_dwordx4 v164, s[60:61]
	s_add_u32 m0, m0, 0x400
	s_nop 0
	global_load_lds_dwordx4 v165, s[60:61]
	v_mov_b32_e32 v110, 0
	v_mov_b32_e32 v111, v110
	v_mov_b32_e32 v112, v110
	v_mov_b32_e32 v113, v110
	v_mov_b32_e32 v90, v110
	v_mov_b32_e32 v91, v110
	v_mov_b32_e32 v92, v110
	v_mov_b32_e32 v93, v110
	v_mov_b32_e32 v40, v110
	v_mov_b32_e32 v41, v110
	v_mov_b32_e32 v42, v110
	v_mov_b32_e32 v43, v110
	v_mov_b32_e32 v44, v110
	v_mov_b32_e32 v45, v110
	v_mov_b32_e32 v46, v110
	v_mov_b32_e32 v47, v110
	v_mov_b32_e32 v48, v110
	v_mov_b32_e32 v49, v110
	v_mov_b32_e32 v50, v110
	v_mov_b32_e32 v51, v110
	v_mov_b32_e32 v52, v110
	v_mov_b32_e32 v53, v110
	v_mov_b32_e32 v54, v110
	v_mov_b32_e32 v55, v110
	v_mov_b32_e32 v56, v110
	v_mov_b32_e32 v57, v110
	v_mov_b32_e32 v58, v110
	v_mov_b32_e32 v59, v110
	v_mov_b32_e32 v60, v110
	v_mov_b32_e32 v61, v110
	v_mov_b32_e32 v62, v110
	v_mov_b32_e32 v63, v110
	v_mov_b32_e32 v64, v110
	v_mov_b32_e32 v65, v110
	v_mov_b32_e32 v66, v110
	v_mov_b32_e32 v67, v110
	v_mov_b32_e32 v68, v110
	v_mov_b32_e32 v69, v110
	v_mov_b32_e32 v70, v110
	v_mov_b32_e32 v71, v110
	v_mov_b32_e32 v72, v110
	v_mov_b32_e32 v73, v110
	v_mov_b32_e32 v74, v110
	v_mov_b32_e32 v75, v110
	v_mov_b32_e32 v76, v110
	v_mov_b32_e32 v34, v110
	v_mov_b32_e32 v35, v110
	v_mov_b32_e32 v36, v110
	v_mov_b32_e32 v37, v110
	v_mov_b32_e32 v38, v110
	v_mov_b32_e32 v39, v110
	v_mov_b32_e32 v77, v110
	v_mov_b32_e32 v78, v110
	v_mov_b32_e32 v79, v110
	v_mov_b32_e32 v80, v110
	v_mov_b32_e32 v81, v110
	v_mov_b32_e32 v82, v110
	v_mov_b32_e32 v83, v110
	v_mov_b32_e32 v84, v110
	v_mov_b32_e32 v85, v110
	v_mov_b32_e32 v86, v110
	v_mov_b32_e32 v87, v110
	v_mov_b32_e32 v88, v110
	v_mov_b32_e32 v89, v110
	v_mov_b32_e32 v94, v110
	v_mov_b32_e32 v95, v110
	v_mov_b32_e32 v96, v110
	v_mov_b32_e32 v97, v110
	v_mov_b32_e32 v98, v110
	v_mov_b32_e32 v99, v110
	v_mov_b32_e32 v100, v110
	v_mov_b32_e32 v101, v110
	v_mov_b32_e32 v102, v110
	v_mov_b32_e32 v103, v110
	v_mov_b32_e32 v104, v110
	v_mov_b32_e32 v105, v110
	v_mov_b32_e32 v106, v110
	v_mov_b32_e32 v107, v110
	v_mov_b32_e32 v108, v110
	v_mov_b32_e32 v109, v110
	v_mov_b32_e32 v114, v110
	v_mov_b32_e32 v115, v110
	v_mov_b32_e32 v116, v110
	v_mov_b32_e32 v117, v110
	v_mov_b32_e32 v118, v110
	v_mov_b32_e32 v119, v110
	v_mov_b32_e32 v120, v110
	v_mov_b32_e32 v121, v110
	v_mov_b32_e32 v122, v110
	v_mov_b32_e32 v123, v110
	v_mov_b32_e32 v124, v110
	v_mov_b32_e32 v125, v110
	v_mov_b32_e32 v126, v110
	v_mov_b32_e32 v127, v110
	v_mov_b32_e32 v128, v110
	v_mov_b32_e32 v129, v110
	v_mov_b32_e32 v130, v110
	v_mov_b32_e32 v131, v110
	v_mov_b32_e32 v132, v110
	v_mov_b32_e32 v133, v110
	v_mov_b32_e32 v134, v110
	v_mov_b32_e32 v135, v110
	v_mov_b32_e32 v136, v110
	v_mov_b32_e32 v137, v110
	v_mov_b32_e32 v138, v110
	v_mov_b32_e32 v139, v110
	v_mov_b32_e32 v140, v110
	v_mov_b32_e32 v141, v110
	v_mov_b32_e32 v142, v110
	v_mov_b32_e32 v143, v110
	v_mov_b32_e32 v144, v110
	v_mov_b32_e32 v145, v110
	v_mov_b32_e32 v146, v110
	v_mov_b32_e32 v147, v110
	v_mov_b32_e32 v148, v110
	v_mov_b32_e32 v149, v110
	v_mov_b32_e32 v150, v110
	v_mov_b32_e32 v151, v110
	v_mov_b32_e32 v152, v110
	v_mov_b32_e32 v153, v110
	v_mov_b32_e32 v154, v110
	v_mov_b32_e32 v155, v110
	v_mov_b32_e32 v156, v110
	v_mov_b32_e32 v157, v110
	v_mov_b32_e32 v158, v110
	v_mov_b32_e32 v159, v110
	v_mov_b32_e32 v160, v110
	v_mov_b32_e32 v161, v110
	s_add_i32 s3, s23, -2
	s_mov_b32 s26, 0
	s_mov_b32 s27, s3
	s_waitcnt vmcnt(4)
	s_barrier
	v_add_u32_e32 v19, v180, v184
	v_add_u32_e32 v18, v180, v183
	ds_read_b128 v[2:5], v19 offset:32768
	ds_read_b128 v[6:9], v19 offset:34816
	ds_read_b128 v[10:13], v19 offset:36864
	ds_read_b128 v[14:17], v19 offset:38912
	ds_read_b128 v[202:205], v18
	ds_read_b128 v[206:209], v18 offset:2048
	ds_read_b128 v[226:229], v18 offset:4096
.LBB0_897:
	s_and_b32 s28, s26, 0x10000
	s_xor_b32 s29, s28, 0x10000
	s_add_u32 m0, s29, s57
	s_add_u32 m0, m0, 0x1000
	v_or_b32_e32 v0, s28, v180
	v_add_u32_e32 v218, v0, v184
	v_add_u32_e32 v0, v0, v183
	s_waitcnt lgkmcnt(2)
	v_mfma_f32_16x16x32_bf16 v[158:161], v[2:5], v[202:205], v[158:161]
	global_load_lds_dwordx4 v166, s[60:61]
	s_add_u32 m0, m0, 0x400
	v_add_u32_e32 v218, v218, v181
	s_add_i32 s27, s27, -1
	v_mfma_f32_16x16x32_bf16 v[154:157], v[6:9], v[202:205], v[154:157]
	s_add_i32 s26, s26, 0x10000
	v_mfma_f32_16x16x32_bf16 v[150:153], v[10:13], v[202:205], v[150:153]
	global_load_lds_dwordx4 v167, s[60:61]
	s_add_u32 m0, m0, 0x400
	v_mfma_f32_16x16x32_bf16 v[146:149], v[14:17], v[202:205], v[146:149]
	ds_read_b128 v[202:205], v0 offset:6144
	s_waitcnt lgkmcnt(2)
	v_mfma_f32_16x16x32_bf16 v[142:145], v[2:5], v[206:209], v[142:145]
	global_load_lds_dwordx4 v168, s[60:61]
	s_add_u32 m0, m0, 0x400
	v_mfma_f32_16x16x32_bf16 v[138:141], v[6:9], v[206:209], v[138:141]
	v_mfma_f32_16x16x32_bf16 v[134:137], v[10:13], v[206:209], v[134:137]
	global_load_lds_dwordx4 v169, s[60:61]
	s_add_u32 s60, s60, 0x80
	s_addc_u32 s61, s61, 0
	v_mfma_f32_16x16x32_bf16 v[130:133], v[14:17], v[206:209], v[130:133]
	ds_read_b128 v[206:209], v0 offset:8192
	s_waitcnt lgkmcnt(2)
	v_mfma_f32_16x16x32_bf16 v[126:129], v[2:5], v[226:229], v[126:129]
	v_mfma_f32_16x16x32_bf16 v[122:125], v[6:9], v[226:229], v[122:125]
	v_mfma_f32_16x16x32_bf16 v[118:121], v[10:13], v[226:229], v[118:121]
	v_mfma_f32_16x16x32_bf16 v[114:117], v[14:17], v[226:229], v[114:117]
	ds_read_b128 v[226:229], v0 offset:10240
	s_waitcnt lgkmcnt(2)
	v_mfma_f32_16x16x32_bf16 v[106:109], v[2:5], v[202:205], v[106:109]
	v_mfma_f32_16x16x32_bf16 v[102:105], v[6:9], v[202:205], v[102:105]
	v_mfma_f32_16x16x32_bf16 v[98:101], v[10:13], v[202:205], v[98:101]
	v_mfma_f32_16x16x32_bf16 v[94:97], v[14:17], v[202:205], v[94:97]
	ds_read_b128 v[202:205], v0 offset:12288
	ds_read_b128 v[230:233], v218 offset:32768
	s_waitcnt lgkmcnt(3)
	v_mfma_f32_16x16x32_bf16 v[86:89], v[2:5], v[206:209], v[86:89]
	v_mfma_f32_16x16x32_bf16 v[82:85], v[6:9], v[206:209], v[82:85]
	v_mfma_f32_16x16x32_bf16 v[78:81], v[10:13], v[206:209], v[78:81]
	v_mfma_f32_16x16x32_bf16 v[74:77], v[14:17], v[206:209], v[74:77]
	ds_read_b128 v[206:209], v0 offset:14336
	ds_read_b128 v[234:237], v218 offset:34816
	v_add_u32_e32 v0, v0, v181
	s_waitcnt lgkmcnt(4)
	v_mfma_f32_16x16x32_bf16 v[70:73], v[2:5], v[226:229], v[70:73]
	v_mfma_f32_16x16x32_bf16 v[66:69], v[6:9], v[226:229], v[66:69]
	v_mfma_f32_16x16x32_bf16 v[62:65], v[10:13], v[226:229], v[62:65]
	v_mfma_f32_16x16x32_bf16 v[58:61], v[14:17], v[226:229], v[58:61]
	ds_read_b128 v[226:229], v0 offset:0
	ds_read_b128 v[238:241], v218 offset:36864
	s_waitcnt lgkmcnt(5)
	v_mfma_f32_16x16x32_bf16 v[54:57], v[2:5], v[202:205], v[54:57]
	v_mfma_f32_16x16x32_bf16 v[50:53], v[6:9], v[202:205], v[50:53]
	v_mfma_f32_16x16x32_bf16 v[46:49], v[10:13], v[202:205], v[46:49]
	v_mfma_f32_16x16x32_bf16 v[42:45], v[14:17], v[202:205], v[42:45]
	ds_read_b128 v[202:205], v0 offset:2048
	ds_read_b128 v[242:245], v218 offset:38912
	s_waitcnt lgkmcnt(5)
	v_mfma_f32_16x16x32_bf16 v[38:41], v[2:5], v[206:209], v[38:41]
	v_mfma_f32_16x16x32_bf16 v[34:37], v[6:9], v[206:209], v[34:37]
	v_mfma_f32_16x16x32_bf16 v[90:93], v[10:13], v[206:209], v[90:93]
	v_mfma_f32_16x16x32_bf16 v[110:113], v[14:17], v[206:209], v[110:113]
	ds_read_b128 v[186:189], v0 offset:4096
	s_waitcnt lgkmcnt(4)
	v_mfma_f32_16x16x32_bf16 v[158:161], v[230:233], v[226:229], v[158:161]
	v_mfma_f32_16x16x32_bf16 v[154:157], v[234:237], v[226:229], v[154:157]
	s_waitcnt lgkmcnt(3)
	v_mfma_f32_16x16x32_bf16 v[150:153], v[238:241], v[226:229], v[150:153]
	s_waitcnt lgkmcnt(1)
	v_mfma_f32_16x16x32_bf16 v[146:149], v[242:245], v[226:229], v[146:149]
	ds_read_b128 v[190:193], v0 offset:6144
	v_mfma_f32_16x16x32_bf16 v[142:145], v[230:233], v[202:205], v[142:145]
	v_mfma_f32_16x16x32_bf16 v[138:141], v[234:237], v[202:205], v[138:141]
	v_mfma_f32_16x16x32_bf16 v[134:137], v[238:241], v[202:205], v[134:137]
	v_mfma_f32_16x16x32_bf16 v[130:133], v[242:245], v[202:205], v[130:133]
	ds_read_b128 v[194:197], v0 offset:8192
	s_waitcnt lgkmcnt(2)
	v_mfma_f32_16x16x32_bf16 v[126:129], v[230:233], v[186:189], v[126:129]
	v_mfma_f32_16x16x32_bf16 v[122:125], v[234:237], v[186:189], v[122:125]
	v_mfma_f32_16x16x32_bf16 v[118:121], v[238:241], v[186:189], v[118:121]
	v_mfma_f32_16x16x32_bf16 v[114:117], v[242:245], v[186:189], v[114:117]
	ds_read_b128 v[186:189], v0 offset:10240
	s_waitcnt lgkmcnt(2)
	v_mfma_f32_16x16x32_bf16 v[106:109], v[230:233], v[190:193], v[106:109]
	v_mfma_f32_16x16x32_bf16 v[102:105], v[234:237], v[190:193], v[102:105]
	v_mfma_f32_16x16x32_bf16 v[98:101], v[238:241], v[190:193], v[98:101]
	v_mfma_f32_16x16x32_bf16 v[94:97], v[242:245], v[190:193], v[94:97]
	ds_read_b128 v[190:193], v0 offset:12288
	s_waitcnt lgkmcnt(2)
	v_mfma_f32_16x16x32_bf16 v[86:89], v[230:233], v[194:197], v[86:89]
	v_mfma_f32_16x16x32_bf16 v[82:85], v[234:237], v[194:197], v[82:85]
	v_mfma_f32_16x16x32_bf16 v[78:81], v[238:241], v[194:197], v[78:81]
	v_mfma_f32_16x16x32_bf16 v[74:77], v[242:245], v[194:197], v[74:77]
	ds_read_b128 v[194:197], v0 offset:14336
	s_waitcnt vmcnt(0) lgkmcnt(0)
	s_barrier
; template <int NT, int BM, int BN, bool PLAIN, int NSTAGE, bool EPI_LDS>
; __device__ __forceinline__ void gemm_tile(const Params& p, const GemmDesc& g, bf16_t* lds, const int tid) {
;     ...
;     if (PLAIN) {
;       int kt = 0;
;       for (; kt + 2 < nk; ++kt) {
;         const int cur = kt & 1;
;         COMPUTE_X(cur, 1, 1, kt + 2)
;         __syncthreads();
;       }
;       if (kt + 1 < nk) {
;         const int cur = kt & 1;
;         COMPUTE_X(cur, 1, 0, 0)
;         __syncthreads();
;         ++kt;
;       }
;       {
;         const int cur = kt & 1;
;         COMPUTE_X(cur, 0, 0, 0)
;         __syncthreads();
	s_xor_b32 s29, s28, 0x10000
	v_or_b32_e32 v18, s29, v180
	v_add_u32_e32 v19, v18, v184
	v_add_u32_e32 v18, v18, v183
	ds_read_b128 v[2:5], v19 offset:32768
	ds_read_b128 v[6:9], v19 offset:34816
	ds_read_b128 v[10:13], v19 offset:36864
	ds_read_b128 v[14:17], v19 offset:38912
	ds_read_b128 v[202:205], v18
	ds_read_b128 v[206:209], v18 offset:2048
	ds_read_b128 v[226:229], v18 offset:4096
	s_add_u32 m0, s28, s57
	v_mfma_f32_16x16x32_bf16 v[70:73], v[230:233], v[186:189], v[70:73]
	global_load_lds_dwordx4 v162, s[60:61]
	s_add_u32 m0, m0, 0x400
	v_mfma_f32_16x16x32_bf16 v[66:69], v[234:237], v[186:189], v[66:69]
	v_mfma_f32_16x16x32_bf16 v[62:65], v[238:241], v[186:189], v[62:65]
	v_mfma_f32_16x16x32_bf16 v[58:61], v[242:245], v[186:189], v[58:61]
	global_load_lds_dwordx4 v163, s[60:61]
	s_add_u32 m0, m0, 0x400
	v_mfma_f32_16x16x32_bf16 v[54:57], v[230:233], v[190:193], v[54:57]
	v_mfma_f32_16x16x32_bf16 v[50:53], v[234:237], v[190:193], v[50:53]
	v_mfma_f32_16x16x32_bf16 v[46:49], v[238:241], v[190:193], v[46:49]
	global_load_lds_dwordx4 v164, s[60:61]
	s_add_u32 m0, m0, 0x400
	v_mfma_f32_16x16x32_bf16 v[42:45], v[242:245], v[190:193], v[42:45]
	v_mfma_f32_16x16x32_bf16 v[38:41], v[230:233], v[194:197], v[38:41]
	v_mfma_f32_16x16x32_bf16 v[34:37], v[234:237], v[194:197], v[34:37]
	global_load_lds_dwordx4 v165, s[60:61]
	v_mfma_f32_16x16x32_bf16 v[90:93], v[238:241], v[194:197], v[90:93]
	v_mfma_f32_16x16x32_bf16 v[110:113], v[242:245], v[194:197], v[110:113]
	s_cmp_lg_u32 s27, 0
	s_cbranch_scc1 .LBB0_897
	s_lshl_b32 s3, s3, 16
	s_and_b32 s3, s3, 0x10000
	s_xor_b32 s29, s3, 0x10000
	s_add_u32 m0, s29, s57
	s_add_u32 m0, m0, 0x1000
	s_nop 0
	global_load_lds_dwordx4 v166, s[60:61]
	s_add_u32 m0, m0, 0x400
	s_nop 0
	global_load_lds_dwordx4 v167, s[60:61]
	s_add_u32 m0, m0, 0x400
	s_nop 0
	global_load_lds_dwordx4 v168, s[60:61]
	s_add_u32 m0, m0, 0x400
	s_nop 0
	global_load_lds_dwordx4 v169, s[60:61]
	v_or_b32_e32 v0, s3, v180
	v_add_u32_e32 v198, v0, v184
	ds_read_b128 v[162:165], v198 offset:32768
	ds_read_b128 v[166:169], v198 offset:34816
	ds_read_b128 v[170:173], v198 offset:36864
	ds_read_b128 v[186:189], v198 offset:38912
	v_add_u32_e32 v0, v0, v183
	ds_read_b128 v[174:177], v0
	ds_read_b128 v[190:193], v0 offset:2048
	ds_read_b128 v[194:197], v0 offset:4096
	s_waitcnt lgkmcnt(2)
	v_mfma_f32_16x16x32_bf16 v[30:33], v[162:165], v[174:177], v[158:161]
	s_not_b32 s3, s23
	s_lshl_b32 s3, s3, 16
	s_and_b32 s3, s3, 0x10000
	v_mfma_f32_16x16x32_bf16 v[154:157], v[166:169], v[174:177], v[154:157]
	s_cmp_lg_u32 s56, 9
	s_cselect_b64 s[26:27], -1, 0
	s_mov_b32 s24, s41
	v_mfma_f32_16x16x32_bf16 v[150:153], v[170:173], v[174:177], v[150:153]
	s_mov_b32 s23, s42
	s_mov_b64 s[28:29], -1
	s_and_b64 vcc, exec, s[26:27]
	v_mfma_f32_16x16x32_bf16 v[146:149], v[186:189], v[174:177], v[146:149]
	ds_read_b128 v[158:161], v0 offset:6144
	v_add_u32_e32 v174, v198, v181
	s_waitcnt lgkmcnt(2)
	v_mfma_f32_16x16x32_bf16 v[26:29], v[162:165], v[190:193], v[142:145]
	v_mfma_f32_16x16x32_bf16 v[138:141], v[166:169], v[190:193], v[138:141]
	v_mfma_f32_16x16x32_bf16 v[134:137], v[170:173], v[190:193], v[134:137]
	v_mfma_f32_16x16x32_bf16 v[130:133], v[186:189], v[190:193], v[130:133]
	ds_read_b128 v[142:145], v0 offset:8192
	s_waitcnt lgkmcnt(2)
	v_mfma_f32_16x16x32_bf16 v[22:25], v[162:165], v[194:197], v[126:129]
	v_mfma_f32_16x16x32_bf16 v[122:125], v[166:169], v[194:197], v[122:125]
	v_mfma_f32_16x16x32_bf16 v[118:121], v[170:173], v[194:197], v[118:121]
	v_mfma_f32_16x16x32_bf16 v[114:117], v[186:189], v[194:197], v[114:117]
	ds_read_b128 v[126:129], v0 offset:10240
	s_waitcnt lgkmcnt(2)
	v_mfma_f32_16x16x32_bf16 v[18:21], v[162:165], v[158:161], v[106:109]
	v_mfma_f32_16x16x32_bf16 v[102:105], v[166:169], v[158:161], v[102:105]
	v_mfma_f32_16x16x32_bf16 v[98:101], v[170:173], v[158:161], v[98:101]
	v_mfma_f32_16x16x32_bf16 v[94:97], v[186:189], v[158:161], v[94:97]
	ds_read_b128 v[106:109], v0 offset:12288
	ds_read_b128 v[158:161], v174 offset:32768
	s_waitcnt lgkmcnt(3)
	v_mfma_f32_16x16x32_bf16 v[14:17], v[162:165], v[142:145], v[86:89]
	v_mfma_f32_16x16x32_bf16 v[82:85], v[166:169], v[142:145], v[82:85]
	v_mfma_f32_16x16x32_bf16 v[78:81], v[170:173], v[142:145], v[78:81]
	v_mfma_f32_16x16x32_bf16 v[74:77], v[186:189], v[142:145], v[74:77]
	ds_read_b128 v[86:89], v0 offset:14336
	ds_read_b128 v[142:145], v174 offset:34816
	v_add_u32_e32 v0, v0, v181
	s_waitcnt lgkmcnt(4)
	v_mfma_f32_16x16x32_bf16 v[10:13], v[162:165], v[126:129], v[70:73]
	v_mfma_f32_16x16x32_bf16 v[66:69], v[166:169], v[126:129], v[66:69]
	v_mfma_f32_16x16x32_bf16 v[62:65], v[170:173], v[126:129], v[62:65]
	v_mfma_f32_16x16x32_bf16 v[58:61], v[186:189], v[126:129], v[58:61]
	ds_read_b128 v[70:73], v0 offset:0
	ds_read_b128 v[126:129], v174 offset:36864
	s_waitcnt lgkmcnt(5)
	v_mfma_f32_16x16x32_bf16 v[6:9], v[162:165], v[106:109], v[54:57]
	v_mfma_f32_16x16x32_bf16 v[50:53], v[166:169], v[106:109], v[50:53]
	v_mfma_f32_16x16x32_bf16 v[46:49], v[170:173], v[106:109], v[46:49]
	v_mfma_f32_16x16x32_bf16 v[42:45], v[186:189], v[106:109], v[42:45]
	ds_read_b128 v[106:109], v174 offset:38912
	ds_read_b128 v[54:57], v0 offset:2048
	s_waitcnt lgkmcnt(5)
	v_mfma_f32_16x16x32_bf16 v[2:5], v[162:165], v[86:89], v[38:41]
	v_mfma_f32_16x16x32_bf16 v[34:37], v[166:169], v[86:89], v[34:37]
	v_mfma_f32_16x16x32_bf16 v[38:41], v[170:173], v[86:89], v[90:93]
	v_mfma_f32_16x16x32_bf16 v[86:89], v[186:189], v[86:89], v[110:113]
	s_nop 1
	ds_read_b128 v[90:93], v0 offset:4096
	s_waitcnt lgkmcnt(4)
	v_mfma_f32_16x16x32_bf16 v[30:33], v[158:161], v[70:73], v[30:33]
	v_mfma_f32_16x16x32_bf16 v[110:113], v[142:145], v[70:73], v[154:157]
	s_waitcnt lgkmcnt(3)
	v_mfma_f32_16x16x32_bf16 v[150:153], v[126:129], v[70:73], v[150:153]
	s_waitcnt lgkmcnt(2)
	v_mfma_f32_16x16x32_bf16 v[70:73], v[106:109], v[70:73], v[146:149]
	s_nop 2
	ds_read_b128 v[146:149], v0 offset:6144
	s_waitcnt lgkmcnt(2)
	v_mfma_f32_16x16x32_bf16 v[26:29], v[158:161], v[54:57], v[26:29]
	v_mfma_f32_16x16x32_bf16 v[138:141], v[142:145], v[54:57], v[138:141]
	v_mfma_f32_16x16x32_bf16 v[134:137], v[126:129], v[54:57], v[134:137]
	v_mfma_f32_16x16x32_bf16 v[54:57], v[106:109], v[54:57], v[130:133]
	s_nop 2
	ds_read_b128 v[130:133], v0 offset:8192
	s_waitcnt lgkmcnt(2)
	v_mfma_f32_16x16x32_bf16 v[22:25], v[158:161], v[90:93], v[22:25]
	v_mfma_f32_16x16x32_bf16 v[122:125], v[142:145], v[90:93], v[122:125]
	v_mfma_f32_16x16x32_bf16 v[118:121], v[126:129], v[90:93], v[118:121]
	v_mfma_f32_16x16x32_bf16 v[90:93], v[106:109], v[90:93], v[114:117]
	s_nop 2
	ds_read_b128 v[114:117], v0 offset:10240
	s_waitcnt lgkmcnt(2)
	v_mfma_f32_16x16x32_bf16 v[18:21], v[158:161], v[146:149], v[18:21]
	v_mfma_f32_16x16x32_bf16 v[102:105], v[142:145], v[146:149], v[102:105]
	v_mfma_f32_16x16x32_bf16 v[98:101], v[126:129], v[146:149], v[98:101]
	v_mfma_f32_16x16x32_bf16 v[94:97], v[106:109], v[146:149], v[94:97]
	ds_read_b128 v[146:149], v0 offset:12288
	s_waitcnt lgkmcnt(2)
	v_mfma_f32_16x16x32_bf16 v[14:17], v[158:161], v[130:133], v[14:17]
	v_mfma_f32_16x16x32_bf16 v[82:85], v[142:145], v[130:133], v[82:85]
	v_mfma_f32_16x16x32_bf16 v[78:81], v[126:129], v[130:133], v[78:81]
	v_mfma_f32_16x16x32_bf16 v[74:77], v[106:109], v[130:133], v[74:77]
	ds_read_b128 v[130:133], v0 offset:14336
	v_or_b32_e32 v0, s3, v180
	v_add_u32_e32 v186, v0, v184
	s_waitcnt lgkmcnt(2)
	v_mfma_f32_16x16x32_bf16 v[10:13], v[158:161], v[114:117], v[10:13]
	s_waitcnt vmcnt(0) lgkmcnt(0)
	s_barrier
; template <int NT, int BM, int BN, bool PLAIN, int NSTAGE, bool EPI_LDS>
; __device__ __forceinline__ void gemm_tile(const Params& p, const GemmDesc& g, bf16_t* lds, const int tid) {
;     ...
;   if (EPI_LDS) {
;     constexpr int CST = BN + 16;
;     bf16_t* ct = lds;
;     const bool relu2 = (g.epi == E_RELU2);
; #pragma unroll
;     for (int mi = 0; mi < MI; ++mi)
; #pragma unroll
;       for (int ni = 0; ni < NI; ++ni) {
;         f32x4 v = acc[mi][ni];
;         if (relu2) {
; #pragma unroll
;           for (int j = 0; j < 4; ++j) { const float r = fmaxf(v[j], 0.f); v[j] = r * r; }
;         }
;         u32x2 w;
;         w[0] = pack2(v[0], v[1]);
;         w[1] = pack2(v[2], v[3]);
;         *(u32x2*)(ct + (wm * WTM + mi * 16 + fr) * CST + wn * WTN + ni * 16 + fq * 4) = w;
;       }
	v_mfma_f32_16x16x32_bf16 v[66:69], v[142:145], v[114:117], v[66:69]
	v_add_u32_e32 v0, v0, v183
	v_mfma_f32_16x16x32_bf16 v[62:65], v[126:129], v[114:117], v[62:65]
	v_mfma_f32_16x16x32_bf16 v[58:61], v[106:109], v[114:117], v[58:61]
	v_mfma_f32_16x16x32_bf16 v[6:9], v[158:161], v[146:149], v[6:9]
	v_mfma_f32_16x16x32_bf16 v[50:53], v[142:145], v[146:149], v[50:53]
	v_mfma_f32_16x16x32_bf16 v[46:49], v[126:129], v[146:149], v[46:49]
	v_mfma_f32_16x16x32_bf16 v[42:45], v[106:109], v[146:149], v[42:45]
	v_mfma_f32_16x16x32_bf16 v[2:5], v[158:161], v[130:133], v[2:5]
	v_mfma_f32_16x16x32_bf16 v[34:37], v[142:145], v[130:133], v[34:37]
	v_mfma_f32_16x16x32_bf16 v[38:41], v[126:129], v[130:133], v[38:41]
	v_mfma_f32_16x16x32_bf16 v[86:89], v[106:109], v[130:133], v[86:89]
	ds_read_b128 v[106:109], v186 offset:32768
	ds_read_b128 v[114:117], v186 offset:34816
	ds_read_b128 v[130:133], v186 offset:36864
	ds_read_b128 v[142:145], v186 offset:38912
	ds_read_b128 v[126:129], v0
	ds_read_b128 v[146:149], v0 offset:2048
	ds_read_b128 v[154:157], v0 offset:4096
	s_waitcnt lgkmcnt(2)
	v_mfma_f32_16x16x32_bf16 v[30:33], v[106:109], v[126:129], v[30:33]
	v_mfma_f32_16x16x32_bf16 v[110:113], v[114:117], v[126:129], v[110:113]
	v_mfma_f32_16x16x32_bf16 v[150:153], v[130:133], v[126:129], v[150:153]
	v_mfma_f32_16x16x32_bf16 v[70:73], v[142:145], v[126:129], v[70:73]
	ds_read_b128 v[126:129], v0 offset:6144
	s_waitcnt lgkmcnt(2)
	v_mfma_f32_16x16x32_bf16 v[26:29], v[106:109], v[146:149], v[26:29]
	v_mfma_f32_16x16x32_bf16 v[138:141], v[114:117], v[146:149], v[138:141]
	v_mfma_f32_16x16x32_bf16 v[134:137], v[130:133], v[146:149], v[134:137]
	v_mfma_f32_16x16x32_bf16 v[54:57], v[142:145], v[146:149], v[54:57]
	ds_read_b128 v[146:149], v0 offset:8192
	s_waitcnt lgkmcnt(2)
	v_mfma_f32_16x16x32_bf16 v[22:25], v[106:109], v[154:157], v[22:25]
	v_mfma_f32_16x16x32_bf16 v[158:161], v[114:117], v[154:157], v[122:125]
	v_mfma_f32_16x16x32_bf16 v[162:165], v[130:133], v[154:157], v[118:121]
	v_mfma_f32_16x16x32_bf16 v[154:157], v[142:145], v[154:157], v[90:93]
	s_nop 2
	ds_read_b128 v[90:93], v0 offset:10240
	s_waitcnt lgkmcnt(2)
	v_mfma_f32_16x16x32_bf16 v[18:21], v[106:109], v[126:129], v[18:21]
	v_mfma_f32_16x16x32_bf16 v[166:169], v[114:117], v[126:129], v[102:105]
	v_mfma_f32_16x16x32_bf16 v[170:173], v[130:133], v[126:129], v[98:101]
	v_mfma_f32_16x16x32_bf16 v[174:177], v[142:145], v[126:129], v[94:97]
	s_nop 1
	v_add_u32_e32 v98, v186, v181
	ds_read_b128 v[186:189], v98 offset:32768
	ds_read_b128 v[94:97], v0 offset:12288
	s_waitcnt lgkmcnt(3)
	v_mfma_f32_16x16x32_bf16 v[14:17], v[106:109], v[146:149], v[14:17]
	v_mfma_f32_16x16x32_bf16 v[190:193], v[114:117], v[146:149], v[82:85]
	v_mfma_f32_16x16x32_bf16 v[194:197], v[130:133], v[146:149], v[78:81]
	v_mfma_f32_16x16x32_bf16 v[146:149], v[142:145], v[146:149], v[74:77]
	ds_read_b128 v[198:201], v98 offset:34816
	s_nop 1
	ds_read_b128 v[74:77], v0 offset:14336
	v_add_u32_e32 v0, v0, v181
	s_waitcnt lgkmcnt(4)
	v_mfma_f32_16x16x32_bf16 v[10:13], v[106:109], v[90:93], v[10:13]
	v_mfma_f32_16x16x32_bf16 v[202:205], v[114:117], v[90:93], v[66:69]
	v_mfma_f32_16x16x32_bf16 v[206:209], v[130:133], v[90:93], v[62:65]
	v_mfma_f32_16x16x32_bf16 v[226:229], v[142:145], v[90:93], v[58:61]
	ds_read_b128 v[230:233], v98 offset:36864
	s_nop 1
	ds_read_b128 v[58:61], v0 offset:0
	s_waitcnt lgkmcnt(4)
	v_mfma_f32_16x16x32_bf16 v[6:9], v[106:109], v[94:97], v[6:9]
	v_mfma_f32_16x16x32_bf16 v[234:237], v[114:117], v[94:97], v[50:53]
	v_mfma_f32_16x16x32_bf16 v[238:241], v[130:133], v[94:97], v[46:49]
	v_mfma_f32_16x16x32_bf16 v[242:245], v[142:145], v[94:97], v[42:45]
	ds_read_b128 v[246:249], v98 offset:38912
	s_nop 1
	ds_read_b128 v[42:45], v0 offset:2048
	s_waitcnt lgkmcnt(4)
	v_mfma_f32_16x16x32_bf16 v[2:5], v[106:109], v[74:77], v[2:5]
	v_mfma_f32_16x16x32_bf16 v[218:221], v[114:117], v[74:77], v[34:37]
	v_mfma_f32_16x16x32_bf16 v[130:133], v[130:133], v[74:77], v[38:41]
	v_mfma_f32_16x16x32_bf16 v[142:145], v[142:145], v[74:77], v[86:89]
	s_nop 0
	ds_read_b128 v[34:37], v0 offset:4096
	s_waitcnt lgkmcnt(3)
	v_mfma_f32_16x16x32_bf16 v[126:129], v[186:189], v[58:61], v[30:33]
	v_mfma_f32_16x16x32_bf16 v[122:125], v[198:201], v[58:61], v[110:113]
	v_mfma_f32_16x16x32_bf16 v[118:121], v[230:233], v[58:61], v[150:153]
	s_waitcnt lgkmcnt(2)
	v_mfma_f32_16x16x32_bf16 v[114:117], v[246:249], v[58:61], v[70:73]
	ds_read_b128 v[30:33], v0 offset:6144
	s_waitcnt lgkmcnt(2)
	v_mfma_f32_16x16x32_bf16 v[110:113], v[186:189], v[42:45], v[26:29]
	v_mfma_f32_16x16x32_bf16 v[106:109], v[198:201], v[42:45], v[138:141]
	v_mfma_f32_16x16x32_bf16 v[102:105], v[230:233], v[42:45], v[134:137]
	v_mfma_f32_16x16x32_bf16 v[98:101], v[246:249], v[42:45], v[54:57]
	ds_read_b128 v[26:29], v0 offset:8192
	s_waitcnt lgkmcnt(2)
	v_mfma_f32_16x16x32_bf16 v[94:97], v[186:189], v[34:37], v[22:25]
	v_mfma_f32_16x16x32_bf16 v[90:93], v[198:201], v[34:37], v[158:161]
	v_mfma_f32_16x16x32_bf16 v[86:89], v[230:233], v[34:37], v[162:165]
	v_mfma_f32_16x16x32_bf16 v[82:85], v[246:249], v[34:37], v[154:157]
	ds_read_b128 v[22:25], v0 offset:10240
	s_waitcnt lgkmcnt(2)
	v_mfma_f32_16x16x32_bf16 v[78:81], v[186:189], v[30:33], v[18:21]
	v_mfma_f32_16x16x32_bf16 v[74:77], v[198:201], v[30:33], v[166:169]
	v_mfma_f32_16x16x32_bf16 v[70:73], v[230:233], v[30:33], v[170:173]
	v_mfma_f32_16x16x32_bf16 v[66:69], v[246:249], v[30:33], v[174:177]
	ds_read_b128 v[18:21], v0 offset:12288
	s_waitcnt lgkmcnt(2)
	v_mfma_f32_16x16x32_bf16 v[62:65], v[186:189], v[26:29], v[14:17]
	v_mfma_f32_16x16x32_bf16 v[58:61], v[198:201], v[26:29], v[190:193]
	v_mfma_f32_16x16x32_bf16 v[54:57], v[230:233], v[26:29], v[194:197]
	v_mfma_f32_16x16x32_bf16 v[50:53], v[246:249], v[26:29], v[146:149]
	ds_read_b128 v[134:137], v0 offset:14336
	s_waitcnt lgkmcnt(0)
	s_barrier
	v_mfma_f32_16x16x32_bf16 v[46:49], v[186:189], v[22:25], v[10:13]
	v_mfma_f32_16x16x32_bf16 v[42:45], v[198:201], v[22:25], v[202:205]
	v_mfma_f32_16x16x32_bf16 v[38:41], v[230:233], v[22:25], v[206:209]
	v_mfma_f32_16x16x32_bf16 v[34:37], v[246:249], v[22:25], v[226:229]
	v_mfma_f32_16x16x32_bf16 v[30:33], v[186:189], v[18:21], v[6:9]
	v_mfma_f32_16x16x32_bf16 v[26:29], v[198:201], v[18:21], v[234:237]
	v_mfma_f32_16x16x32_bf16 v[22:25], v[230:233], v[18:21], v[238:241]
	v_mfma_f32_16x16x32_bf16 v[18:21], v[246:249], v[18:21], v[242:245]
	v_mfma_f32_16x16x32_bf16 v[14:17], v[186:189], v[134:137], v[2:5]
	v_mfma_f32_16x16x32_bf16 v[10:13], v[198:201], v[134:137], v[218:221]
	v_mfma_f32_16x16x32_bf16 v[2:5], v[230:233], v[134:137], v[130:133]
	v_mfma_f32_16x16x32_bf16 v[6:9], v[246:249], v[134:137], v[142:145]
	s_cbranch_vccz .LBB0_900
	s_nop 0
	v_cvt_pk_bf16_f32 v130, v126, v127
	v_cvt_pk_bf16_f32 v131, v128, v129
	s_mov_b64 s[28:29], 0
